# grid barriers 0..4 split into arrive / transpose-slice / wait: the phase-0 weight-transpose rounds 1..10 run in 2-round slices between the arrive and the wait of barriers 0..4 (round 0 with the GEMV t
# speedup vs baseline: 1.0133x; 1.0047x over previous
.LBB0_126:
	s_cmp_lt_i32 s88, 1
	s_cbranch_scc0 .Lsl0_out
	s_cmp_gt_i32 s89, 0
	s_cbranch_scc0 .Lsl0_out
	s_load_dword s4, s[0:1], 0x120
	s_load_dwordx16 s[52:67], s[0:1], 0x0
	s_load_dwordx16 s[68:83], s[0:1], 0x80
	s_waitcnt lgkmcnt(0)
	s_lshl_b32 s4, s4, 1
	s_mul_i32 s5, s4, 1
	s_lshl_b32 s33, s2, 1
	s_add_i32 s33, s33, s5
	s_cmp_eq_u32 s89, 18
	s_cselect_b32 s5, 3, 11
	s_mul_i32 s4, s4, s5
	s_min_u32 s4, s4, 0x15d0
	s_cmp_ge_i32 s33, s4
	s_cbranch_scc1 .Lsl0_out
	s_add_u32 s94, s34, 0x1da0000
	s_addc_u32 s95, s35, 0
	v_writelane_b32 v252, s90, 0
	s_add_u32 s4, s34, 0x7a0000
	s_addc_u32 s5, s35, 0
	v_writelane_b32 v252, s91, 1
	v_writelane_b32 v252, s4, 2
	v_lshrrev_b32_e32 v138, 8, v204
	v_and_b32_e32 v139, 0xff, v204
	v_writelane_b32 v252, s5, 3
	s_add_u32 s4, s34, 0x720000
	s_addc_u32 s5, s35, 0
	v_writelane_b32 v252, s4, 4
	v_mul_u32_u24_e32 v140, 0x12000, v138
	v_mov_b32_e32 v129, 0
	v_writelane_b32 v252, s5, 5
	s_add_u32 s4, s34, 0x520000
	s_addc_u32 s5, s35, 0
	s_add_u32 s90, s34, 0x4a0000
	s_addc_u32 s91, s35, 0
	s_add_u32 s96, s34, 0x440000
	s_addc_u32 s97, s35, 0
	s_add_u32 s16, s34, 0x28a0000
	s_addc_u32 s17, s35, 0
	s_add_u32 s18, s0, 0x120
	v_writelane_b32 v252, s4, 6
	s_addc_u32 s19, s1, 0
	s_movk_i32 s8, 0x104
	s_movk_i32 s9, 0xffe0
	s_movk_i32 s10, 0x6000
	s_movk_i32 s11, 0x400
	s_mov_b32 s12, 0xbfb8aa3b
	s_mov_b32 s13, 0x42ce8ed0
	s_mov_b32 s14, 0xc2b17218
	s_movk_i32 s15, 0x1800
	v_mov_b32_e32 v141, 0xfffffd40
	v_mov_b32_e32 v142, 0xb00000
	v_mov_b32_e32 v143, 0x580000
	v_mov_b32_e32 v144, 0x7f800000
	v_writelane_b32 v252, s5, 7
	s_branch .Lsl0_22

.Lsl0_21:
	s_or_b64 exec, exec, s[20:21]
	s_waitcnt lgkmcnt(0)
	s_load_dword s4, s[18:19], 0x0
	s_waitcnt lgkmcnt(0)
	s_lshl_b32 s4, s4, 1
	s_add_i32 s33, s4, s33
	s_cmp_eq_u32 s89, 18
	s_cselect_b32 s5, 3, 11
	s_mul_i32 s4, s4, s5
	s_min_u32 s4, s4, 0x15d0
	s_cmp_lt_i32 s33, s4
	s_cbranch_scc0 .Lsl0_71

.LBB0_189:
	s_cmp_lg_u32 s88, 0
	s_cbranch_scc1 .Lsl1_out
	s_cmp_lg_u32 s89, 18
	s_cbranch_scc1 .Lsl1_out
	s_load_dword s4, s[0:1], 0x120
	s_load_dwordx16 s[52:67], s[0:1], 0x0
	s_load_dwordx16 s[68:83], s[0:1], 0x80
	s_waitcnt lgkmcnt(0)
	s_lshl_b32 s4, s4, 1
	s_mul_i32 s5, s4, 3
	s_lshl_b32 s33, s2, 1
	s_add_i32 s33, s33, s5
	s_mov_b32 s5, 5
	s_mul_i32 s4, s4, s5
	s_min_u32 s4, s4, 0x15d0
	s_cmp_ge_i32 s33, s4
	s_cbranch_scc1 .Lsl1_out
	s_add_u32 s94, s34, 0x1da0000
	s_addc_u32 s95, s35, 0
	v_writelane_b32 v252, s90, 0
	s_add_u32 s4, s34, 0x7a0000
	s_addc_u32 s5, s35, 0
	v_writelane_b32 v252, s91, 1
	v_writelane_b32 v252, s4, 2
	v_lshrrev_b32_e32 v138, 8, v204
	v_and_b32_e32 v139, 0xff, v204
	v_writelane_b32 v252, s5, 3
	s_add_u32 s4, s34, 0x720000
	s_addc_u32 s5, s35, 0
	v_writelane_b32 v252, s4, 4
	v_mul_u32_u24_e32 v140, 0x12000, v138
	v_mov_b32_e32 v129, 0
	v_writelane_b32 v252, s5, 5
	s_add_u32 s4, s34, 0x520000
	s_addc_u32 s5, s35, 0
	s_add_u32 s90, s34, 0x4a0000
	s_addc_u32 s91, s35, 0
	s_add_u32 s96, s34, 0x440000
	s_addc_u32 s97, s35, 0
	s_add_u32 s16, s34, 0x28a0000
	s_addc_u32 s17, s35, 0
	s_add_u32 s18, s0, 0x120
	v_writelane_b32 v252, s4, 6
	s_addc_u32 s19, s1, 0
	s_movk_i32 s8, 0x104
	s_movk_i32 s9, 0xffe0
	s_movk_i32 s10, 0x6000
	s_movk_i32 s11, 0x400
	s_mov_b32 s12, 0xbfb8aa3b
	s_mov_b32 s13, 0x42ce8ed0
	s_mov_b32 s14, 0xc2b17218
	s_movk_i32 s15, 0x1800
	v_mov_b32_e32 v141, 0xfffffd40
	v_mov_b32_e32 v142, 0xb00000
	v_mov_b32_e32 v143, 0x580000
	v_mov_b32_e32 v144, 0x7f800000
	v_writelane_b32 v252, s5, 7
	s_branch .Lsl1_22

.Lsl1_21:
	s_or_b64 exec, exec, s[20:21]
	s_waitcnt lgkmcnt(0)
	s_load_dword s4, s[18:19], 0x0
	s_waitcnt lgkmcnt(0)
	s_lshl_b32 s4, s4, 1
	s_add_i32 s33, s4, s33
	s_mov_b32 s5, 5
	s_mul_i32 s4, s4, s5
	s_min_u32 s4, s4, 0x15d0
	s_cmp_lt_i32 s33, s4
	s_cbranch_scc0 .Lsl1_71

.Lsl1_out:
	s_cmp_gt_i32 s88, 1
	s_cbranch_scc1 .Lsb1_skip
	s_cmp_lt_i32 s89, 3
	s_cbranch_scc1 .Lsb1_skip
	s_waitcnt vmcnt(0) lgkmcnt(0)
	s_and_saveexec_b64 s[16:17], s[92:93]
	s_cbranch_execz .Lsb1_done
	v_mov_b32_e32 v0, 0x24008
	ds_read_b32 v1, v0
	buffer_inv sc1
	s_add_u32 s18, s34, 0xed10500
	s_addc_u32 s19, s35, 0
	v_mov_b32_e32 v0, 0
	s_mov_b32 s20, 0
	s_waitcnt lgkmcnt(0)

.Lsb1_skip:
	s_cmp_gt_i32 s89, 2
	s_cselect_b64 s[4:5], -1, 0
	s_waitcnt lgkmcnt(0)
	s_cmp_lt_i32 s88, 3
	s_cselect_b64 s[18:19], -1, 0
	s_and_b64 s[4:5], s[18:19], s[4:5]
	s_andn2_b64 vcc, exec, s[4:5]
	s_cbranch_vccnz .LBB0_426
	s_add_u32 s16, s34, 0x28c4000
	s_addc_u32 s17, s35, 0
	s_add_u32 s6, s34, 0x8a44000
	s_addc_u32 s7, s35, 0
	s_add_u32 s8, s0, 0x120
	s_addc_u32 s9, s1, 0
	s_cmpk_lt_i32 s2, 0x100
	s_cbranch_scc0 .LBB0_197
	s_load_dword s9, s[0:1], 0x120
	v_readfirstlane_b32 s42, v205
	v_and_b32_e32 v192, 15, v204
	v_bfe_u32 v193, v204, 4, 2
	v_lshrrev_b32_e32 v194, 8, v204
	v_bfe_u32 v195, v204, 6, 2
	v_bfe_u32 v196, v204, 1, 3
	v_xor_b32_e32 v197, v193, v196
	v_xor_b32_e32 v198, 4, v197
	v_lshlrev_b32_e32 v197, 4, v197
	v_lshlrev_b32_e32 v198, 4, v198
	v_lshlrev_b32_e32 v199, 14, v194
	v_lshl_add_u32 v199, v192, 7, v199
	v_add_u32_e32 v242, v199, v197
	v_add_u32_e32 v243, v199, v198
	v_lshlrev_b32_e32 v199, 13, v195
	v_lshl_add_u32 v199, v192, 7, v199
	v_add_u32_e32 v199, 0x8000, v199
	v_add_u32_e32 v244, v199, v197
	v_add_u32_e32 v245, v199, v198
	v_add_u32_e32 v246, 0x10000, v242
	v_add_u32_e32 v248, 0x10000, v244
	v_add_u32_e32 v247, 0x10000, v243
	v_add_u32_e32 v249, 0x10000, v245
	v_lshrrev_b32_e32 v199, 3, v204
	v_and_b32_e32 v200, 7, v204
	v_bfe_u32 v201, v204, 4, 3
	v_xor_b32_e32 v200, v200, v201
	v_lshlrev_b32_e32 v200, 4, v200
	v_lshl_add_u32 v238, v199, 11, v200
	v_add_u32_e32 v239, 0x20000, v238
	v_add_u32_e32 v240, 0x40000, v238
	v_add_u32_e32 v241, 0x60000, v238
	s_lshl_b32 s42, s42, 10
	s_mov_b32 s8, s2
	s_and_b32 s44, s8, 7
	s_lshl_b32 s44, s44, 5
	s_lshr_b32 s45, s8, 3
	s_add_i32 s44, s44, s45
	s_lshr_b32 s45, s44, 6
	s_and_b32 s44, s44, 63
	s_and_b32 s98, s44, 7
	s_lshl_b32 s45, s45, 3
	s_add_i32 s45, s45, s98
	s_lshl_b32 s14, s45, 8
	s_lshr_b32 s44, s44, 3
	s_lshl_b32 s15, s44, 8
	s_mul_i32 s44, s14, 0x800
	s_add_u32 s44, s44, 0x8a44000
	s_add_u32 s10, s34, s44
	s_addc_u32 s11, s35, 0
	s_mul_i32 s44, s15, 0x800
	s_add_u32 s44, s44, 0x0
	s_add_u32 s12, s34, s44
	s_addc_u32 s13, s35, 0
	s_waitcnt vmcnt(0) lgkmcnt(0)
	s_barrier
	s_add_u32 m0, s42, 0x0
	s_nop 0
	global_load_lds_dwordx4 v238, s[10:11]
	s_add_u32 m0, s42, 0x2000
	s_nop 0
	global_load_lds_dwordx4 v239, s[10:11]
	s_add_u32 m0, s42, 0x4000
	s_nop 0
	global_load_lds_dwordx4 v240, s[10:11]
	s_add_u32 m0, s42, 0x6000
	s_nop 0
	global_load_lds_dwordx4 v241, s[10:11]
	s_add_u32 m0, s42, 0x8000
	s_nop 0
	global_load_lds_dwordx4 v238, s[12:13]
	s_add_u32 m0, s42, 0xa000
	s_nop 0
	global_load_lds_dwordx4 v239, s[12:13]
	s_add_u32 m0, s42, 0xc000
	s_nop 0
	global_load_lds_dwordx4 v240, s[12:13]
	s_add_u32 m0, s42, 0xe000
	s_nop 0
	global_load_lds_dwordx4 v241, s[12:13]
	s_waitcnt vmcnt(0)
	s_nop 0

.LBB0_480:
	s_cmp_lg_u32 s88, 0
	s_cbranch_scc1 .Lsl2_out
	s_cmp_lg_u32 s89, 18
	s_cbranch_scc1 .Lsl2_out
	s_load_dword s4, s[0:1], 0x120
	s_load_dwordx16 s[52:67], s[0:1], 0x0
	s_load_dwordx16 s[68:83], s[0:1], 0x80
	s_waitcnt lgkmcnt(0)
	s_lshl_b32 s4, s4, 1
	s_mul_i32 s5, s4, 5
	s_lshl_b32 s33, s2, 1
	s_add_i32 s33, s33, s5
	s_mov_b32 s5, 7
	s_mul_i32 s4, s4, s5
	s_min_u32 s4, s4, 0x15d0
	s_cmp_ge_i32 s33, s4
	s_cbranch_scc1 .Lsl2_out
	s_add_u32 s94, s34, 0x1da0000
	s_addc_u32 s95, s35, 0
	v_writelane_b32 v252, s90, 0
	s_add_u32 s4, s34, 0x7a0000
	s_addc_u32 s5, s35, 0
	v_writelane_b32 v252, s91, 1
	v_writelane_b32 v252, s4, 2
	v_lshrrev_b32_e32 v138, 8, v204
	v_and_b32_e32 v139, 0xff, v204
	v_writelane_b32 v252, s5, 3
	s_add_u32 s4, s34, 0x720000
	s_addc_u32 s5, s35, 0
	v_writelane_b32 v252, s4, 4
	v_mul_u32_u24_e32 v140, 0x12000, v138
	v_mov_b32_e32 v129, 0
	v_writelane_b32 v252, s5, 5
	s_add_u32 s4, s34, 0x520000
	s_addc_u32 s5, s35, 0
	s_add_u32 s90, s34, 0x4a0000
	s_addc_u32 s91, s35, 0
	s_add_u32 s96, s34, 0x440000
	s_addc_u32 s97, s35, 0
	s_add_u32 s16, s34, 0x28a0000
	s_addc_u32 s17, s35, 0
	s_add_u32 s18, s0, 0x120
	v_writelane_b32 v252, s4, 6
	s_addc_u32 s19, s1, 0
	s_movk_i32 s8, 0x104
	s_movk_i32 s9, 0xffe0
	s_movk_i32 s10, 0x6000
	s_movk_i32 s11, 0x400
	s_mov_b32 s12, 0xbfb8aa3b
	s_mov_b32 s13, 0x42ce8ed0
	s_mov_b32 s14, 0xc2b17218
	s_movk_i32 s15, 0x1800
	v_mov_b32_e32 v141, 0xfffffd40
	v_mov_b32_e32 v142, 0xb00000
	v_mov_b32_e32 v143, 0x580000
	v_mov_b32_e32 v144, 0x7f800000
	v_writelane_b32 v252, s5, 7
	s_branch .Lsl2_22

.Lsl2_21:
	s_or_b64 exec, exec, s[20:21]
	s_waitcnt lgkmcnt(0)
	s_load_dword s4, s[18:19], 0x0
	s_waitcnt lgkmcnt(0)
	s_lshl_b32 s4, s4, 1
	s_add_i32 s33, s4, s33
	s_mov_b32 s5, 7
	s_mul_i32 s4, s4, s5
	s_min_u32 s4, s4, 0x15d0
	s_cmp_lt_i32 s33, s4
	s_cbranch_scc0 .Lsl2_71

.Lsl2_out:
	s_cmp_gt_i32 s88, 2
	s_cbranch_scc1 .Lsb2_skip
	s_cmp_lt_i32 s89, 4
	s_cbranch_scc1 .Lsb2_skip
	s_waitcnt vmcnt(0) lgkmcnt(0)
	s_and_saveexec_b64 s[16:17], s[92:93]
	s_cbranch_execz .Lsb2_done
	v_mov_b32_e32 v0, 0x24008
	ds_read_b32 v1, v0
	buffer_inv sc1
	s_add_u32 s18, s34, 0xed10500
	s_addc_u32 s19, s35, 0
	v_mov_b32_e32 v0, 0
	s_mov_b32 s20, 0
	s_waitcnt lgkmcnt(0)

.Lsb2_skip:
	s_cmp_gt_i32 s89, 3
	s_cselect_b64 s[4:5], -1, 0
	s_waitcnt lgkmcnt(0)
	s_cmp_lt_i32 s88, 4
	s_cselect_b64 s[16:17], -1, 0
	s_and_b64 s[4:5], s[16:17], s[4:5]
	s_andn2_b64 vcc, exec, s[4:5]
	s_cbranch_vccnz .LBB0_561
	s_waitcnt vmcnt(6)
	v_lshl_add_u32 v4, s2, 3, v205
	s_movk_i32 s4, 0x1fff
	v_cmp_lt_i32_e32 vcc, s4, v4
	s_and_saveexec_b64 s[6:7], vcc
	s_xor_b64 s[6:7], exec, s[6:7]
	s_add_u32 s4, s0, 0x120
	s_addc_u32 s5, s1, 0
	s_or_saveexec_b64 s[18:19], s[6:7]
	v_mov_b64_e32 v[0:1], s[4:5]
	s_xor_b64 exec, exec, s[18:19]
	s_cbranch_execz .LBB0_505
	v_mbcnt_lo_u32_b32 v3, -1, 0
	v_mbcnt_hi_u32_b32 v3, -1, v3
	v_and_b32_e32 v5, 64, v3
	v_add_u32_e32 v5, 64, v5
	v_xor_b32_e32 v6, 32, v3
	v_cmp_lt_i32_e32 vcc, v6, v5
	s_mov_b32 s6, 0xc2fc0000
	s_waitcnt vmcnt(5)
	v_mov_b32_e32 v8, 0x42800000
	v_cndmask_b32_e32 v6, v3, v6, vcc
	v_lshlrev_b32_e32 v35, 2, v6
	v_xor_b32_e32 v6, 16, v3
	v_cmp_lt_i32_e32 vcc, v6, v5
	s_load_dword s12, s[0:1], 0x120
	s_add_u32 s10, s34, 0x28c4000
	v_cndmask_b32_e32 v6, v3, v6, vcc
	v_lshlrev_b32_e32 v40, 2, v6
	v_xor_b32_e32 v6, 8, v3
	v_cmp_lt_i32_e32 vcc, v6, v5
	s_addc_u32 s11, s35, 0
	v_and_b32_e32 v1, 15, v204
	v_cndmask_b32_e32 v6, v3, v6, vcc
	v_lshlrev_b32_e32 v41, 2, v6
	v_xor_b32_e32 v6, 4, v3
	v_cmp_lt_i32_e32 vcc, v6, v5
	s_load_dwordx16 s[36:51], s[0:1], 0x40
	v_and_b32_e32 v0, 63, v204
	v_cndmask_b32_e32 v6, v3, v6, vcc
	v_lshlrev_b32_e32 v42, 2, v6
	v_xor_b32_e32 v6, 2, v3
	v_cmp_lt_i32_e32 vcc, v6, v5
	v_mov_b32_e32 v7, 0
	s_add_u32 s20, s0, 0x120
	v_cndmask_b32_e32 v6, v3, v6, vcc
	v_lshlrev_b32_e32 v43, 2, v6
	v_xor_b32_e32 v6, 1, v3
	v_cmp_lt_i32_e32 vcc, v6, v5
	s_addc_u32 s21, s1, 0
	s_waitcnt lgkmcnt(0)
	s_lshl_b32 s14, s12, 3
	v_cndmask_b32_e32 v3, v3, v6, vcc
	v_lshlrev_b32_e32 v44, 2, v3
	v_and_b32_e32 v3, 7, v204
	v_cvt_f32_ubyte0_e32 v5, v3
	v_mul_f32_e32 v6, 0xbfd49a78, v5
	v_cmp_gt_f32_e32 vcc, s6, v6
	s_mov_b64 s[12:13], 0x4944000
	s_waitcnt vmcnt(4)
	v_lshlrev_b32_e32 v14, 3, v0
	v_cndmask_b32_e32 v6, 0, v8, vcc
	v_fmac_f32_e32 v6, 0xbfd49a78, v5
	v_exp_f32_e32 v5, v6
	v_not_b32_e32 v6, 63
	v_cndmask_b32_e32 v6, 0, v6, vcc
	v_mov_b32_e32 v15, v7
	v_ldexp_f32 v45, v5, v6
	v_lshlrev_b32_e32 v6, 2, v1
	v_lshl_add_u64 v[10:11], s[34:35], 0, v[6:7]
	v_lshl_add_u64 v[10:11], v[10:11], 0, s[12:13]
	s_waitcnt vmcnt(3)
	v_lshl_add_u64 v[18:19], s[34:35], 0, v[14:15]
	s_mov_b64 s[12:13], 0xc744000
	v_lshlrev_b32_e32 v5, 10, v204
	v_lshlrev_b32_e32 v6, 4, v0
	v_lshl_add_u64 v[14:15], v[18:19], 0, s[12:13]
	s_mov_b64 s[12:13], 0xcb44000
	v_cmp_gt_u32_e64 s[8:9], 8, v1
	v_and_b32_e32 v8, 0x2000, v5
	v_lshl_add_u64 v[12:13], s[50:51], 0, v[6:7]
	v_lshl_add_u64 v[16:17], s[70:71], 0, v[6:7]
	v_lshl_add_u64 v[18:19], v[18:19], 0, s[12:13]
	s_waitcnt vmcnt(2)
	v_lshl_add_u64 v[20:21], s[86:87], 0, v[6:7]
	s_mov_b64 s[12:13], 0x2000000
	v_lshlrev_b32_e32 v6, 1, v0
	v_mov_b32_e32 v1, s81
	v_mov_b32_e32 v5, s79
	v_cmp_gt_u32_e32 vcc, 8, v0
	v_lshl_add_u64 v[20:21], v[20:21], 0, s[12:13]
	v_lshl_add_u64 v[22:23], s[34:35], 0, v[6:7]
	s_mov_b64 s[12:13], 0xcf84000
	s_waitcnt vmcnt(1)
	v_cndmask_b32_e32 v25, v1, v5, vcc
	v_mov_b32_e32 v1, s80
	v_mov_b32_e32 v5, s78
	v_lshlrev_b32_e32 v6, 2, v3
	v_lshlrev_b32_e32 v2, 2, v0
	v_and_b32_e32 v32, 31, v204
	v_lshl_add_u64 v[22:23], v[22:23], 0, s[12:13]
	v_cndmask_b32_e32 v24, v1, v5, vcc
	v_lshl_add_u64 v[26:27], s[34:35], 0, v[6:7]
	s_mov_b64 s[12:13], 0xec0c000
	v_cmp_gt_u32_e64 s[4:5], 32, v0
	v_cmp_gt_u32_e64 s[6:7], 16, v0
	v_mov_b32_e32 v9, v7
	v_lshl_add_u64 v[24:25], v[24:25], 0, v[6:7]
	v_lshl_add_u64 v[26:27], v[26:27], 0, s[12:13]
	s_mov_b64 s[22:23], 0
	s_movk_i32 s15, 0x1000
	s_movk_i32 s25, 0xfff
	s_movk_i32 s30, 0x1100
	s_movk_i32 s31, 0x1040
	s_waitcnt vmcnt(0)
	v_mov_b64_e32 v[28:29], s[10:11]
	v_lshlrev_b32_e32 v30, 1, v2
	v_mov_b32_e32 v31, v7
	v_lshlrev_b32_e32 v32, 1, v32
	v_mov_b32_e32 v33, v7
	s_mov_b32 s24, 0x3b800000
	v_mov_b32_e32 v34, 0x358637bd
	s_mov_b32 s33, 0x800000
	v_lshlrev_b32_e32 v6, 2, v0
	s_mov_b32 s42, 0x41a00000
	s_mov_b32 s43, 0x3fb8aa3b
	s_mov_b32 s44, 0xc2ce8ed0
	s_mov_b32 s45, 0x42b17218
	s_mov_b32 s48, 0x7f800000
	s_mov_b32 s49, 0x3f2aaaab
	v_mov_b32_e32 v46, 0x3ecc95a3
	s_mov_b32 s50, 0x3f317218
	s_mov_b32 s51, 0x33800000
	s_movk_i32 s56, 0x1fff
	v_mov_b32_e32 v47, 0x7f800000
	v_mov_b32_e32 v36, 0x3f317218
	s_branch .LBB0_487

.LBB0_615:
	s_cmp_lg_u32 s88, 0
	s_cbranch_scc1 .Lsl3_out
	s_cmp_lg_u32 s89, 18
	s_cbranch_scc1 .Lsl3_out
	s_load_dword s4, s[0:1], 0x120
	s_load_dwordx16 s[52:67], s[0:1], 0x0
	s_load_dwordx16 s[68:83], s[0:1], 0x80
	s_waitcnt lgkmcnt(0)
	s_lshl_b32 s4, s4, 1
	s_mul_i32 s5, s4, 7
	s_lshl_b32 s33, s2, 1
	s_add_i32 s33, s33, s5
	s_mov_b32 s5, 9
	s_mul_i32 s4, s4, s5
	s_min_u32 s4, s4, 0x15d0
	s_cmp_ge_i32 s33, s4
	s_cbranch_scc1 .Lsl3_out
	s_add_u32 s94, s34, 0x1da0000
	s_addc_u32 s95, s35, 0
	v_writelane_b32 v252, s90, 0
	s_add_u32 s4, s34, 0x7a0000
	s_addc_u32 s5, s35, 0
	v_writelane_b32 v252, s91, 1
	v_writelane_b32 v252, s4, 2
	v_lshrrev_b32_e32 v138, 8, v204
	v_and_b32_e32 v139, 0xff, v204
	v_writelane_b32 v252, s5, 3
	s_add_u32 s4, s34, 0x720000
	s_addc_u32 s5, s35, 0
	v_writelane_b32 v252, s4, 4
	v_mul_u32_u24_e32 v140, 0x12000, v138
	v_mov_b32_e32 v129, 0
	v_writelane_b32 v252, s5, 5
	s_add_u32 s4, s34, 0x520000
	s_addc_u32 s5, s35, 0
	s_add_u32 s90, s34, 0x4a0000
	s_addc_u32 s91, s35, 0
	s_add_u32 s96, s34, 0x440000
	s_addc_u32 s97, s35, 0
	s_add_u32 s16, s34, 0x28a0000
	s_addc_u32 s17, s35, 0
	s_add_u32 s18, s0, 0x120
	v_writelane_b32 v252, s4, 6
	s_addc_u32 s19, s1, 0
	s_movk_i32 s8, 0x104
	s_movk_i32 s9, 0xffe0
	s_movk_i32 s10, 0x6000
	s_movk_i32 s11, 0x400
	s_mov_b32 s12, 0xbfb8aa3b
	s_mov_b32 s13, 0x42ce8ed0
	s_mov_b32 s14, 0xc2b17218
	s_movk_i32 s15, 0x1800
	v_mov_b32_e32 v141, 0xfffffd40
	v_mov_b32_e32 v142, 0xb00000
	v_mov_b32_e32 v143, 0x580000
	v_mov_b32_e32 v144, 0x7f800000
	v_writelane_b32 v252, s5, 7
	s_branch .Lsl3_22

.Lsl3_21:
	s_or_b64 exec, exec, s[20:21]
	s_waitcnt lgkmcnt(0)
	s_load_dword s4, s[18:19], 0x0
	s_waitcnt lgkmcnt(0)
	s_lshl_b32 s4, s4, 1
	s_add_i32 s33, s4, s33
	s_mov_b32 s5, 9
	s_mul_i32 s4, s4, s5
	s_min_u32 s4, s4, 0x15d0
	s_cmp_lt_i32 s33, s4
	s_cbranch_scc0 .Lsl3_71

.Lsl3_out:
	s_cmp_gt_i32 s88, 3
	s_cbranch_scc1 .Lsb3_skip
	s_cmp_lt_i32 s89, 5
	s_cbranch_scc1 .Lsb3_skip
	s_waitcnt vmcnt(0) lgkmcnt(0)
	s_and_saveexec_b64 s[16:17], s[92:93]
	s_cbranch_execz .Lsb3_done
	v_mov_b32_e32 v0, 0x24008
	ds_read_b32 v1, v0
	buffer_inv sc1
	s_add_u32 s18, s34, 0xed10500
	s_addc_u32 s19, s35, 0
	v_mov_b32_e32 v0, 0
	s_mov_b32 s20, 0
	s_waitcnt lgkmcnt(0)

.Lsb3_skip:
	s_cmp_gt_i32 s89, 4
	s_cselect_b64 s[4:5], -1, 0
	s_waitcnt lgkmcnt(0)
	s_cmp_lt_i32 s88, 5
	s_cselect_b64 s[12:13], -1, 0
	s_and_b64 s[4:5], s[12:13], s[4:5]
	s_andn2_b64 vcc, exec, s[4:5]
	s_cbranch_vccnz .LBB0_790
	s_load_dword s14, s[0:1], 0x120
	v_lshrrev_b32_e32 v97, 8, v204
	v_mul_u32_u24_e32 v96, 0x12000, v97
	s_waitcnt lgkmcnt(0)
	s_cmpk_lg_i32 s14, 0x100
	s_cselect_b64 s[4:5], -1, 0
	s_waitcnt vmcnt(7)
	v_cndmask_b32_e64 v0, 0, 1, s[4:5]
	s_nop 0
	v_readfirstlane_b32 s6, v0
	s_lshl_b32 s28, s2, s6
	s_cmpk_gt_i32 s28, 0x39f
	s_cbranch_scc1 .LBB0_757
	v_and_b32_e32 v0, 0x300, v204
	v_cndmask_b32_e64 v36, v0, v97, s[4:5]
	v_add_u32_e32 v0, s28, v36
	s_waitcnt vmcnt(6)
	v_min_i32_e32 v5, 0x39f, v0
	s_movk_i32 s6, 0x17f
	v_and_b32_e32 v37, 0xff, v204
	v_cmp_lt_i32_e32 vcc, s6, v0
	v_and_b32_e32 v6, 7, v5
	s_and_saveexec_b64 s[6:7], vcc
	s_xor_b64 s[6:7], exec, s[6:7]
	s_cbranch_execz .LBB0_619
	v_add_u32_e32 v0, 0xfffffe80, v5
	v_lshrrev_b32_e32 v0, 3, v0
	s_movk_i32 s8, 0x44
	v_mad_u32_u24 v0, v6, s8, v0
	v_lshrrev_b32_e32 v1, 3, v0
	v_and_b32_e32 v1, 0x7fffff8, v1
	v_sub_u32_e32 v2, 0x44, v1
	v_min_u32_e32 v2, 8, v2
	v_cvt_f32_ubyte0_e32 v3, v2
	v_rcp_iflag_f32_e32 v4, v3
	v_and_b32_e32 v0, 63, v0
	v_cvt_f32_ubyte0_e32 v5, v0
	v_mov_b32_e32 v111, 0
	v_mul_f32_e32 v4, v5, v4
	v_trunc_f32_e32 v4, v4
	v_cvt_u32_f32_e32 v6, v4
	v_fma_f32 v4, -v4, v3, v5
	v_cmp_ge_f32_e64 vcc, |v4|, v3
	s_nop 1
	v_addc_co_u32_e32 v3, vcc, 0, v6, vcc
	v_mul_lo_u16_e32 v2, v3, v2
	v_sub_u16_e32 v0, v0, v2
	v_and_b32_e32 v0, 0xff, v0
	v_and_b32_e32 v4, 0xff, v3
	v_add_lshl_u32 v110, v1, v0, 7

.LBB0_844:
	s_cmp_lg_u32 s88, 0
	s_cbranch_scc1 .Lsl4_out
	s_cmp_lg_u32 s89, 18
	s_cbranch_scc1 .Lsl4_out
	s_load_dword s4, s[0:1], 0x120
	s_load_dwordx16 s[52:67], s[0:1], 0x0
	s_load_dwordx16 s[68:83], s[0:1], 0x80
	s_waitcnt lgkmcnt(0)
	s_lshl_b32 s4, s4, 1
	s_mul_i32 s5, s4, 9
	s_lshl_b32 s33, s2, 1
	s_add_i32 s33, s33, s5
	s_mov_b32 s5, 11
	s_mul_i32 s4, s4, s5
	s_min_u32 s4, s4, 0x15d0
	s_cmp_ge_i32 s33, s4
	s_cbranch_scc1 .Lsl4_out
	s_add_u32 s94, s34, 0x1da0000
	s_addc_u32 s95, s35, 0
	v_writelane_b32 v252, s90, 0
	s_add_u32 s4, s34, 0x7a0000
	s_addc_u32 s5, s35, 0
	v_writelane_b32 v252, s91, 1
	v_writelane_b32 v252, s4, 2
	v_lshrrev_b32_e32 v138, 8, v204
	v_and_b32_e32 v139, 0xff, v204
	v_writelane_b32 v252, s5, 3
	s_add_u32 s4, s34, 0x720000
	s_addc_u32 s5, s35, 0
	v_writelane_b32 v252, s4, 4
	v_mul_u32_u24_e32 v140, 0x12000, v138
	v_mov_b32_e32 v129, 0
	v_writelane_b32 v252, s5, 5
	s_add_u32 s4, s34, 0x520000
	s_addc_u32 s5, s35, 0
	s_add_u32 s90, s34, 0x4a0000
	s_addc_u32 s91, s35, 0
	s_add_u32 s96, s34, 0x440000
	s_addc_u32 s97, s35, 0
	s_add_u32 s16, s34, 0x28a0000
	s_addc_u32 s17, s35, 0
	s_add_u32 s18, s0, 0x120
	v_writelane_b32 v252, s4, 6
	s_addc_u32 s19, s1, 0
	s_movk_i32 s8, 0x104
	s_movk_i32 s9, 0xffe0
	s_movk_i32 s10, 0x6000
	s_movk_i32 s11, 0x400
	s_mov_b32 s12, 0xbfb8aa3b
	s_mov_b32 s13, 0x42ce8ed0
	s_mov_b32 s14, 0xc2b17218
	s_movk_i32 s15, 0x1800
	v_mov_b32_e32 v141, 0xfffffd40
	v_mov_b32_e32 v142, 0xb00000
	v_mov_b32_e32 v143, 0x580000
	v_mov_b32_e32 v144, 0x7f800000
	v_writelane_b32 v252, s5, 7
	s_branch .Lsl4_22

.Lsl4_21:
	s_or_b64 exec, exec, s[20:21]
	s_waitcnt lgkmcnt(0)
	s_load_dword s4, s[18:19], 0x0
	s_waitcnt lgkmcnt(0)
	s_lshl_b32 s4, s4, 1
	s_add_i32 s33, s4, s33
	s_mov_b32 s5, 11
	s_mul_i32 s4, s4, s5
	s_min_u32 s4, s4, 0x15d0
	s_cmp_lt_i32 s33, s4
	s_cbranch_scc0 .Lsl4_71
